# phase 0: each workgroup normalises the 64 rows whose GEMM1 tiles run on its own XCD (on top of the XCD-aligned final phase)
# baseline (speedup 1.0000x reference)
.Lp0_nokm:
	v_lshrrev_b32_e32 v0, 2, v198
	s_mov_b32 s20, 0xc040
	v_mul_lo_u32 v0, v0, s20
	v_and_b32_e32 v1, 3, v198
	v_lshl_add_u32 v0, v1, 4, v0
	s_add_u32 s18, s10, 0x4000
	s_addc_u32 s19, s11, 0
	global_load_dwordx4 v[4:7], v0, s[18:19]
	s_add_u32 s18, s18, 0x602000
	s_addc_u32 s19, s19, 0
	global_load_dwordx4 v[8:11], v0, s[18:19]
	s_add_u32 s18, s18, 0x602000
	s_addc_u32 s19, s19, 0
	global_load_dwordx4 v[12:15], v0, s[18:19]
	s_add_u32 s18, s18, 0x602000
	s_addc_u32 s19, s19, 0
	global_load_dwordx4 v[16:19], v0, s[18:19]
	s_add_u32 s18, s18, 0x602000
	s_addc_u32 s19, s19, 0
	global_load_dwordx4 v[20:23], v0, s[18:19]
	s_add_u32 s18, s18, 0x602000
	s_addc_u32 s19, s19, 0
	global_load_dwordx4 v[24:27], v0, s[18:19]
	s_add_u32 s18, s18, 0x602000
	s_addc_u32 s19, s19, 0
	global_load_dwordx4 v[28:31], v0, s[18:19]
	s_add_u32 s18, s18, 0x602000
	s_addc_u32 s19, s19, 0
	global_load_dwordx4 v[32:35], v0, s[18:19]
	s_add_u32 s18, s18, 0x602000
	s_addc_u32 s19, s19, 0
	global_load_dwordx4 v[36:39], v0, s[18:19]
	s_add_u32 s18, s18, 0x602000
	s_addc_u32 s19, s19, 0
	global_load_dwordx4 v[40:43], v0, s[18:19]
	s_add_u32 s18, s18, 0x602000
	s_addc_u32 s19, s19, 0
	global_load_dwordx4 v[44:47], v0, s[18:19]
	s_add_u32 s18, s18, 0x602000
	s_addc_u32 s19, s19, 0
	global_load_dwordx4 v[48:51], v0, s[18:19]
	s_add_u32 s18, s18, 0x602000
	s_addc_u32 s19, s19, 0
	global_load_dwordx4 v[52:55], v0, s[18:19]
	s_add_u32 s18, s18, 0x602000
	s_addc_u32 s19, s19, 0
	global_load_dwordx4 v[56:59], v0, s[18:19]
	s_add_u32 s18, s18, 0x602000
	s_addc_u32 s19, s19, 0
	global_load_dwordx4 v[60:63], v0, s[18:19]
	s_add_u32 s18, s18, 0x602000
	s_addc_u32 s19, s19, 0
	global_load_dwordx4 v[64:67], v0, s[18:19]
	s_add_u32 s32, s8, 0x1000
	s_addc_u32 s33, s9, 0
	global_load_dwordx4 v[200:203], v166, s[8:9] offset:0
	global_load_dwordx4 v[204:207], v166, s[8:9] offset:1024
	global_load_dwordx4 v[208:211], v166, s[8:9] offset:2048
	global_load_dwordx4 v[212:215], v166, s[8:9] offset:3072
	global_load_dwordx4 v[216:219], v166, s[32:33] offset:0
	global_load_dwordx4 v[220:223], v166, s[32:33] offset:1024
	global_load_dwordx4 v[224:227], v166, s[32:33] offset:2048
	global_load_dwordx4 v[228:231], v166, s[32:33] offset:3072
	v_bfe_u32 v2, v198, 2, 2
	v_lshrrev_b32_e32 v3, 4, v198
	v_lshl_add_u32 v2, v2, 6, v3
	v_lshlrev_b32_e32 v2, 6, v2
	v_add_u32_e32 v3, v1, v196
	v_and_b32_e32 v3, 3, v3
	v_lshl_add_u32 v2, v3, 4, v2
	s_waitcnt vmcnt(23)
	ds_write_b128 v2, v[4:7] offset:0
	s_waitcnt vmcnt(22)
	ds_write_b128 v2, v[8:11] offset:2048
	s_waitcnt vmcnt(21)
	ds_write_b128 v2, v[12:15] offset:16384
	s_waitcnt vmcnt(20)
	ds_write_b128 v2, v[16:19] offset:18432
	s_waitcnt vmcnt(19)
	ds_write_b128 v2, v[20:23] offset:32768
	s_waitcnt vmcnt(18)
	ds_write_b128 v2, v[24:27] offset:34816
	s_waitcnt vmcnt(17)
	ds_write_b128 v2, v[28:31] offset:49152
	s_waitcnt vmcnt(16)
	ds_write_b128 v2, v[32:35] offset:51200
	s_waitcnt vmcnt(15)
	v_add_u32_e32 v3, 0x10000, v2
	ds_write_b128 v3, v[36:39] offset:0
	s_waitcnt vmcnt(14)
	ds_write_b128 v3, v[40:43] offset:2048
	s_waitcnt vmcnt(13)
	ds_write_b128 v3, v[44:47] offset:16384
	s_waitcnt vmcnt(12)
	ds_write_b128 v3, v[48:51] offset:18432
	s_waitcnt vmcnt(11)
	ds_write_b128 v3, v[52:55] offset:32768
	s_waitcnt vmcnt(10)
	ds_write_b128 v3, v[56:59] offset:34816
	s_waitcnt vmcnt(9)
	ds_write_b128 v3, v[60:63] offset:49152
	s_waitcnt vmcnt(8)
	ds_write_b128 v3, v[64:67] offset:51200
	v_lshrrev_b32_e32 v0, 2, v197
	v_add_u32_e32 v1, 0, v0
	v_and_b32_e32 v1, 3, v1
	v_lshlrev_b32_e32 v1, 4, v1
	v_lshl_add_u32 v244, v197, 6, v1
	v_add_u32_e32 v248, 0x10000, v244
	v_add_u32_e32 v1, 1, v0
	v_and_b32_e32 v1, 3, v1
	v_lshlrev_b32_e32 v1, 4, v1
	v_lshl_add_u32 v245, v197, 6, v1
	v_add_u32_e32 v249, 0x10000, v245
	v_add_u32_e32 v1, 2, v0
	v_and_b32_e32 v1, 3, v1
	v_lshlrev_b32_e32 v1, 4, v1
	v_lshl_add_u32 v246, v197, 6, v1
	v_add_u32_e32 v250, 0x10000, v246
	v_add_u32_e32 v1, 3, v0
	v_and_b32_e32 v1, 3, v1
	v_lshlrev_b32_e32 v1, 4, v1
	v_lshl_add_u32 v247, v197, 6, v1
	v_add_u32_e32 v251, 0x10000, v247
	v_and_b32_e32 v0, 32, v197
	v_cmp_ne_u32_e64 s[24:25], 0, v0
	v_and_b32_e32 v0, 16, v197
	v_cmp_ne_u32_e64 s[26:27], 0, v0
	v_and_b32_e32 v0, 8, v197
	v_cmp_ne_u32_e64 s[28:29], 0, v0
	v_and_b32_e32 v0, 4, v197
	v_cmp_ne_u32_e64 s[30:31], 0, v0
	v_and_b32_e32 v0, 2, v197
	v_cmp_ne_u32_e64 s[34:35], 0, v0
	v_bfe_u32 v0, v197, 1, 3
	v_lshlrev_b32_e32 v0, 2, v0
	global_load_dword v237, v0, s[36:37]
	global_load_dword v195, v0, s[38:39]
	s_waitcnt vmcnt(0) lgkmcnt(0)
	v_mul_f32_e32 v237, 0x3fb8aa3b, v237
	v_exp_f32_e32 v237, v237
	s_mov_b32 s20, 0x3a000000
	s_barrier
	v_readfirstlane_b32 s18, v196
	s_and_b32 s16, s96, 7
	s_lshl_b32 s16, s16, 11
	s_lshr_b32 s19, s96, 3
	s_lshl_b32 s19, s19, 6
	s_add_u32 s16, s16, s19
	s_lshl_b32 s18, s18, 3
	s_add_u32 s16, s16, s18
	s_lshl_b32 s18, s16, 13
	s_add_u32 s22, s4, s18
	s_addc_u32 s23, s5, 0
	s_add_u32 s32, s22, 0x1000
	s_addc_u32 s33, s23, 0
	global_load_dwordx4 v[64:67], v166, s[22:23] offset:0 nt
	global_load_dwordx4 v[68:71], v166, s[22:23] offset:1024 nt
	global_load_dwordx4 v[72:75], v166, s[22:23] offset:2048 nt
	global_load_dwordx4 v[76:79], v166, s[22:23] offset:3072 nt
	global_load_dwordx4 v[80:83], v166, s[32:33] offset:0 nt
	global_load_dwordx4 v[84:87], v166, s[32:33] offset:1024 nt
	global_load_dwordx4 v[88:91], v166, s[32:33] offset:2048 nt
	global_load_dwordx4 v[92:95], v166, s[32:33] offset:3072 nt
	s_add_u32 s22, s22, 0x2000
	s_addc_u32 s23, s23, 0
	s_add_u32 s32, s22, 0x1000
	s_addc_u32 s33, s23, 0
	global_load_dwordx4 v[96:99], v166, s[22:23] offset:0 nt
	global_load_dwordx4 v[100:103], v166, s[22:23] offset:1024 nt
	global_load_dwordx4 v[104:107], v166, s[22:23] offset:2048 nt
	global_load_dwordx4 v[108:111], v166, s[22:23] offset:3072 nt
	global_load_dwordx4 v[112:115], v166, s[32:33] offset:0 nt
	global_load_dwordx4 v[116:119], v166, s[32:33] offset:1024 nt
	global_load_dwordx4 v[120:123], v166, s[32:33] offset:2048 nt
	global_load_dwordx4 v[124:127], v166, s[32:33] offset:3072 nt
	s_mov_b32 s17, 0
